# prologue adaLN items: the 36 conditioning values per thread fetched with all loads in flight (was two at a time behind 18 serial waits), silu loop reads them from LDS
# speedup vs baseline: 1.0046x; 1.0046x over previous
; DI void adaln_item(const Params& p, int item, char* smem) {
;     ...
;     for (int i = tid; i < 9 * 1024; i += 256) {
;         const int r = i >> 10, k = i & 1023;
;         const float v = r < 8 ? p.c[r * 1024 + k] : p.c_ctx[k];
;         sc[i] = v / (1.f + expf(-v));
;     }
.LBB0_305:
	v_mov_b32_e32 v32, v200
	s_movk_i32 s4, 0x2400
	s_nop 0
	v_cmp_gt_i32_e32 vcc, s4, v32
	s_and_saveexec_b64 s[4:5], vcc
	s_cbranch_execz .LBB0_313
	s_load_dwordx2 s[8:9], s[0:1], 0x8
	s_load_dwordx2 s[6:7], s[0:1], 0x18
	v_max_i32_e32 v0, 0x2300, v32
	v_sub_u32_e32 v0, v0, v32
	v_add_u32_e32 v1, 0xff, v0
	s_movk_i32 s28, 0xff
	v_cmp_lt_u32_e32 vcc, s28, v1
	s_mov_b64 s[34:35], -1
	v_mov_b32_e32 v0, v32
	s_and_saveexec_b64 s[28:29], vcc
	s_cbranch_execz .LBB0_310
	v_lshrrev_b32_e32 v0, 8, v1
	v_add_u32_e32 v2, 1, v0
	v_and_b32_e32 v3, 0x1fffffe, v2
	s_waitcnt lgkmcnt(0)
	v_add_u32_e32 v33, 0x100, v32
	v_lshl_add_u32 v4, v32, 2, 32
	s_mov_b64 s[34:35], 0
	v_mov_b32_e32 v5, v3
	v_mov_b64_e32 v[0:1], v[32:33]
	v_lshlrev_b32_e32 v184, 2, v32
	v_add_u32_e32 v185, 0x0, v184
	global_load_dword v148, v185, s[8:9]
	v_add_u32_e32 v185, 0x400, v184
	global_load_dword v149, v185, s[8:9]
	v_add_u32_e32 v185, 0x800, v184
	global_load_dword v150, v185, s[8:9]
	v_add_u32_e32 v185, 0xc00, v184
	global_load_dword v151, v185, s[8:9]
	v_add_u32_e32 v185, 0x1000, v184
	global_load_dword v152, v185, s[8:9]
	v_add_u32_e32 v185, 0x1400, v184
	global_load_dword v153, v185, s[8:9]
	v_add_u32_e32 v185, 0x1800, v184
	global_load_dword v154, v185, s[8:9]
	v_add_u32_e32 v185, 0x1c00, v184
	global_load_dword v155, v185, s[8:9]
	v_add_u32_e32 v185, 0x2000, v184
	global_load_dword v156, v185, s[8:9]
	v_add_u32_e32 v185, 0x2400, v184
	global_load_dword v157, v185, s[8:9]
	v_add_u32_e32 v185, 0x2800, v184
	global_load_dword v158, v185, s[8:9]
	v_add_u32_e32 v185, 0x2c00, v184
	global_load_dword v159, v185, s[8:9]
	v_add_u32_e32 v185, 0x3000, v184
	global_load_dword v160, v185, s[8:9]
	v_add_u32_e32 v185, 0x3400, v184
	global_load_dword v161, v185, s[8:9]
	v_add_u32_e32 v185, 0x3800, v184
	global_load_dword v162, v185, s[8:9]
	v_add_u32_e32 v185, 0x3c00, v184
	global_load_dword v163, v185, s[8:9]
	v_add_u32_e32 v185, 0x4000, v184
	global_load_dword v164, v185, s[8:9]
	v_add_u32_e32 v185, 0x4400, v184
	global_load_dword v165, v185, s[8:9]
	v_add_u32_e32 v185, 0x4800, v184
	global_load_dword v166, v185, s[8:9]
	v_add_u32_e32 v185, 0x4c00, v184
	global_load_dword v167, v185, s[8:9]
	v_add_u32_e32 v185, 0x5000, v184
	global_load_dword v168, v185, s[8:9]
	v_add_u32_e32 v185, 0x5400, v184
	global_load_dword v169, v185, s[8:9]
	v_add_u32_e32 v185, 0x5800, v184
	global_load_dword v170, v185, s[8:9]
	v_add_u32_e32 v185, 0x5c00, v184
	global_load_dword v171, v185, s[8:9]
	v_add_u32_e32 v185, 0x6000, v184
	global_load_dword v172, v185, s[8:9]
	v_add_u32_e32 v185, 0x6400, v184
	global_load_dword v173, v185, s[8:9]
	v_add_u32_e32 v185, 0x6800, v184
	global_load_dword v174, v185, s[8:9]
	v_add_u32_e32 v185, 0x6c00, v184
	global_load_dword v175, v185, s[8:9]
	v_add_u32_e32 v185, 0x7000, v184
	global_load_dword v176, v185, s[8:9]
	v_add_u32_e32 v185, 0x7400, v184
	global_load_dword v177, v185, s[8:9]
	v_add_u32_e32 v185, 0x7800, v184
	global_load_dword v178, v185, s[8:9]
	v_add_u32_e32 v185, 0x7c00, v184
	global_load_dword v179, v185, s[8:9]
	v_add_u32_e32 v185, 0x0, v184
	global_load_dword v180, v185, s[6:7]
	v_add_u32_e32 v185, 0x400, v184
	global_load_dword v181, v185, s[6:7]
	v_add_u32_e32 v185, 0x800, v184
	global_load_dword v182, v185, s[6:7]
	v_add_u32_e32 v185, 0xc00, v184
	global_load_dword v183, v185, s[6:7]
	s_waitcnt vmcnt(0)
	ds_write_b32 v4, v148 offset:0
	ds_write_b32 v4, v149 offset:1024
	ds_write_b32 v4, v150 offset:2048
	ds_write_b32 v4, v151 offset:3072
	ds_write_b32 v4, v152 offset:4096
	ds_write_b32 v4, v153 offset:5120
	ds_write_b32 v4, v154 offset:6144
	ds_write_b32 v4, v155 offset:7168
	ds_write_b32 v4, v156 offset:8192
	ds_write_b32 v4, v157 offset:9216
	ds_write_b32 v4, v158 offset:10240
	ds_write_b32 v4, v159 offset:11264
	ds_write_b32 v4, v160 offset:12288
	ds_write_b32 v4, v161 offset:13312
	ds_write_b32 v4, v162 offset:14336
	ds_write_b32 v4, v163 offset:15360
	ds_write_b32 v4, v164 offset:16384
	ds_write_b32 v4, v165 offset:17408
	ds_write_b32 v4, v166 offset:18432
	ds_write_b32 v4, v167 offset:19456
	ds_write_b32 v4, v168 offset:20480
	ds_write_b32 v4, v169 offset:21504
	ds_write_b32 v4, v170 offset:22528
	ds_write_b32 v4, v171 offset:23552
	ds_write_b32 v4, v172 offset:24576
	ds_write_b32 v4, v173 offset:25600
	ds_write_b32 v4, v174 offset:26624
	ds_write_b32 v4, v175 offset:27648
	ds_write_b32 v4, v176 offset:28672
	ds_write_b32 v4, v177 offset:29696
	ds_write_b32 v4, v178 offset:30720
	ds_write_b32 v4, v179 offset:31744
	ds_write_b32 v4, v180 offset:32768
	ds_write_b32 v4, v181 offset:33792
	ds_write_b32 v4, v182 offset:34816
	ds_write_b32 v4, v183 offset:35840
.LBB0_308:
	v_add_u32_e32 v5, -2, v5
	v_add_u32_e32 v0, 0x200, v0
	ds_read2st64_b32 v[8:9], v4 offset1:4
	s_nop 0
	v_cmp_eq_u32_e32 vcc, 0, v5
	s_or_b64 s[34:35], vcc, s[34:35]
	v_add_u32_e32 v1, 0x200, v1
	s_waitcnt lgkmcnt(0)
	v_mul_f32_e32 v6, 0xbfb8aa3b, v8
	v_mul_f32_e32 v7, 0xbfb8aa3b, v9
	v_fma_f32 v10, v8, s37, -v6
	v_rndne_f32_e32 v11, v6
	v_fma_f32 v12, v9, s37, -v7
	v_rndne_f32_e32 v13, v7
	v_fmac_f32_e32 v10, 0xb2a5705f, v8
	v_sub_f32_e32 v6, v6, v11
	v_fmac_f32_e32 v12, 0xb2a5705f, v9
	v_sub_f32_e32 v7, v7, v13
	v_add_f32_e32 v6, v6, v10
	v_cvt_i32_f32_e32 v11, v11
	v_exp_f32_e32 v6, v6
	v_add_f32_e32 v7, v7, v12
	v_cvt_i32_f32_e32 v13, v13
	v_exp_f32_e32 v7, v7
	v_ldexp_f32 v6, v6, v11
	v_cmp_nlt_f32_e32 vcc, s31, v8
	v_cmp_nlt_f32_e64 s[40:41], s31, v9
	v_ldexp_f32 v7, v7, v13
	v_cndmask_b32_e32 v6, 0, v6, vcc
	v_cmp_ngt_f32_e32 vcc, s67, v8
	v_cndmask_b32_e64 v7, 0, v7, s[40:41]
	s_nop 0
	v_cndmask_b32_e32 v6, v209, v6, vcc
	v_cmp_ngt_f32_e32 vcc, s67, v9
	s_nop 1
	v_cndmask_b32_e32 v7, v209, v7, vcc
	v_pk_add_f32 v[6:7], v[6:7], 1.0 op_sel_hi:[1,0]
	s_nop 0
	v_div_scale_f32 v10, s[40:41], v7, v7, v9
	v_div_scale_f32 v12, s[40:41], v6, v6, v8
	v_rcp_f32_e32 v14, v10
	v_rcp_f32_e32 v15, v12
	v_div_scale_f32 v11, vcc, v9, v7, v9
	v_fma_f32 v16, -v10, v14, 1.0
	v_fma_f32 v17, -v12, v15, 1.0
	v_fmac_f32_e32 v14, v16, v14
	v_div_scale_f32 v13, s[40:41], v8, v6, v8
	v_fmac_f32_e32 v15, v17, v15
	v_mul_f32_e32 v16, v11, v14
	v_mul_f32_e32 v17, v13, v15
	v_fma_f32 v18, -v10, v16, v11
	v_fma_f32 v19, -v12, v17, v13
	v_fmac_f32_e32 v16, v18, v14
	v_fmac_f32_e32 v17, v19, v15
	v_fma_f32 v10, -v10, v16, v11
	v_fma_f32 v11, -v12, v17, v13
	v_div_fmas_f32 v10, v10, v14, v16
	s_mov_b64 vcc, s[40:41]
	v_div_fixup_f32 v7, v10, v7, v9
	v_div_fmas_f32 v9, v11, v15, v17
	v_div_fixup_f32 v6, v9, v6, v8
	ds_write2st64_b32 v4, v6, v7 offset1:4
	v_add_u32_e32 v4, 0x800, v4
	s_andn2_b64 exec, exec, s[34:35]
	s_cbranch_execnz .LBB0_308
	s_or_b64 exec, exec, s[34:35]
	v_cmp_ne_u32_e32 vcc, v2, v3
	v_lshl_add_u32 v0, v3, 8, v32
	s_orn2_b64 s[34:35], vcc, exec
